# odd mixer: two task queues (hyena / swa) with per-workgroup start role from wave slot parity
# speedup vs baseline: 1.0189x; 1.0012x over previous
.LBB0_960:
	s_cmp_ge_i32 s2, s18
	s_cselect_b64 s[8:9], -1, 0
	s_and_b64 s[0:1], s[8:9], s[0:1]
	s_andn2_b64 vcc, exec, s[0:1]
	v_writelane_b32 v255, s48, 18
	s_cbranch_vccnz .LBB0_1324
	v_readlane_b32 s0, v255, 7
	v_readlane_b32 s1, v255, 8
	s_mov_b32 s1, s3
	s_mov_b32 s2, s0
	s_lshl_b64 s[0:1], s[0:1], 2
	v_writelane_b32 v255, s2, 7
	s_add_u32 s0, s16, s0
	s_addc_u32 s1, s17, s1
	v_writelane_b32 v255, s3, 8
	v_writelane_b32 v255, s0, 19
	s_and_b64 vcc, exec, s[44:45]
	s_nop 0
	v_writelane_b32 v255, s1, 20
	s_mov_b64 s[0:1], -1
	s_cbranch_vccz .LBB0_1043
	s_and_b64 s[0:1], s[86:87], exec
	v_writelane_b32 v255, s82, 23
	s_movk_i32 s0, 0xa00
	s_cselect_b32 s36, 0x200, s33
	v_writelane_b32 v255, s83, 24
	s_cselect_b32 s37, s0, 0xd00
	s_lshl_b32 s0, s46, 3
	v_writelane_b32 v255, s0, 21
	s_mov_b32 s0, s46
	v_writelane_b32 v255, s0, 25
	s_mov_b64 s[82:83], s[86:87]
	s_mov_b64 s[86:87], s[54:55]
	v_writelane_b32 v255, s1, 26
	s_lshl_b32 s0, s46, 12
	s_add_u32 s8, s12, s0
	s_addc_u32 s9, s13, 0
	s_getreg_b32 s100, hwreg(HW_REG_HW_ID, 0, 4)
	s_and_b32 s100, s100, 1
	s_mov_b32 s101, 0
	s_branch .LBB0_966

.LBB0_966:
	s_waitcnt vmcnt(63) expcnt(7) lgkmcnt(15)
	s_barrier
	s_mov_b64 s[0:1], exec
	v_readlane_b32 s10, v252, 8
	v_readlane_b32 s11, v252, 9
	s_and_b64 s[10:11], s[0:1], s[10:11]
	s_mov_b64 exec, s[10:11]
	s_cbranch_execz .LBB0_970
	s_waitcnt vmcnt(0)
	v_readlane_b32 s10, v255, 19
	v_readlane_b32 s11, v255, 20
	s_nop 4
.Lq_retry:
	v_mov_b32_e32 v2, 1
	s_cmp_eq_u32 s100, 0
	s_cbranch_scc0 .Lq_s
	global_atomic_add v2, v1, v2, s[10:11] offset:12 sc0
	s_branch .Lq_got
.Lq_s:
	global_atomic_add v2, v1, v2, s[10:11] offset:812 sc0
.Lq_got:
	s_waitcnt vmcnt(0)
	v_readfirstlane_b32 s2, v2
	s_sub_i32 s38, s37, s36
	s_cmp_eq_u32 s100, 0
	s_cselect_b32 s38, s36, s38
	s_cmp_lt_i32 s2, s38
	s_cbranch_scc1 .Lq_ok
	s_xor_b32 s100, s100, 1
	s_add_i32 s101, s101, 1
	s_cmp_lt_i32 s101, 2
	s_cbranch_scc1 .Lq_retry
	s_mov_b32 s2, 0x7fffffff
	s_branch .Lq_wr
.Lq_ok:
	s_cmp_eq_u32 s100, 0
	s_cselect_b32 s38, 0, s36
	s_add_i32 s2, s2, s38
.Lq_wr:
	v_mov_b32_e32 v0, s2
	ds_write_b32 v1, v0 offset:8
